# PEER stage C: gather row addresses via one v_mad_u32_u16 per row + SGPR-base loads (7 fewer VALU per 4-row block in the VALU-bound loop)
# baseline (speedup 1.0000x reference)
.LBB0_804:
	v_mov_b32_e32 v0, v175
	s_andn2_b64 vcc, exec, s[56:57]
	s_waitcnt lgkmcnt(0)
	s_cbranch_vccnz .LBB0_761
	v_mov_b32_e32 v170, 0x400
	v_lshlrev_b32_e32 v171, 4, v175
	v_lshlrev_b32_e32 v34, 2, v0
	v_ashrrev_i32_e32 v35, 31, v34
	v_lshlrev_b32_e32 v2, 4, v0
	v_lshlrev_b64 v[0:1], 2, v[34:35]
	v_ashrrev_i32_e32 v3, 31, v2
	v_lshl_add_u64 v[36:37], s[28:29], 0, v[0:1]
	v_lshl_add_u64 v[32:33], s[34:35], 0, v[2:3]
	v_lshl_add_u64 v[38:39], v[36:37], 0, s[46:47]
	v_lshl_add_u64 v[40:41], v[36:37], 0, s[48:49]
	v_lshl_add_u64 v[42:43], v[36:37], 0, s[50:51]
	v_lshl_add_u64 v[44:45], v[36:37], 0, s[52:53]
	v_lshl_add_u64 v[46:47], s[30:31], 0, v[0:1]
	s_mov_b32 s8, 0
	s_mov_b32 s9, s79
	s_mov_b32 s10, s78
	s_branch .LBB0_807

.LBB0_808:
	v_add_u32_e32 v16, s15, v176
	ds_read_b64 v[16:17], v16 offset:2560
	s_waitcnt lgkmcnt(0)
	v_mad_u32_u16 v28, v16, v170, v171
	v_mad_u32_u16 v24, v16, v170, v171 op_sel:[1,0,0,0]
	v_mad_u32_u16 v20, v17, v170, v171
	v_mad_u32_u16 v16, v17, v170, v171 op_sel:[1,0,0,0]
	global_load_dwordx4 v[28:31], v28, s[34:35]
	global_load_dwordx4 v[24:27], v24, s[34:35]
	global_load_dwordx4 v[20:23], v20, s[34:35]
	global_load_dwordx4 v[16:19], v16, s[34:35]
	v_add_u32_e32 v113, s17, v176
	ds_read_b128 v[114:117], v113
	s_waitcnt vmcnt(7)
	v_cvt_scalef32_pk_f32_fp4 v[118:119], v12, 1.0
	s_waitcnt lgkmcnt(0)
	v_pk_fma_f32 v[80:81], v[118:119], v[114:115], v[80:81] op_sel_hi:[1,0,1]
	v_cvt_scalef32_pk_f32_fp4 v[118:119], v12, 1.0 op_sel:[1,0,0]
	v_pk_fma_f32 v[82:83], v[118:119], v[114:115], v[82:83] op_sel_hi:[1,0,1]
	v_cvt_scalef32_pk_f32_fp4 v[118:119], v12, 1.0 op_sel:[0,1,0]
	v_pk_fma_f32 v[84:85], v[118:119], v[114:115], v[84:85] op_sel_hi:[1,0,1]
	v_cvt_scalef32_pk_f32_fp4 v[118:119], v12, 1.0 op_sel:[1,1,0]
	v_pk_fma_f32 v[86:87], v[118:119], v[114:115], v[86:87] op_sel_hi:[1,0,1]
	v_cvt_scalef32_pk_f32_fp4 v[118:119], v13, 1.0
	v_pk_fma_f32 v[88:89], v[118:119], v[114:115], v[88:89] op_sel_hi:[1,0,1]
	v_cvt_scalef32_pk_f32_fp4 v[118:119], v13, 1.0 op_sel:[1,0,0]
	v_pk_fma_f32 v[90:91], v[118:119], v[114:115], v[90:91] op_sel_hi:[1,0,1]
	v_cvt_scalef32_pk_f32_fp4 v[118:119], v13, 1.0 op_sel:[0,1,0]
	v_cvt_scalef32_pk_f32_fp4 v[12:13], v13, 1.0 op_sel:[1,1,0]
	v_pk_fma_f32 v[12:13], v[12:13], v[114:115], v[94:95] op_sel_hi:[1,0,1]
	v_cvt_scalef32_pk_f32_fp4 v[94:95], v14, 1.0
	v_pk_fma_f32 v[94:95], v[94:95], v[114:115], v[96:97] op_sel_hi:[1,0,1]
	v_cvt_scalef32_pk_f32_fp4 v[96:97], v14, 1.0 op_sel:[1,0,0]
	v_pk_fma_f32 v[96:97], v[96:97], v[114:115], v[98:99] op_sel_hi:[1,0,1]
	v_cvt_scalef32_pk_f32_fp4 v[98:99], v14, 1.0 op_sel:[0,1,0]
	v_pk_fma_f32 v[98:99], v[98:99], v[114:115], v[100:101] op_sel_hi:[1,0,1]
	v_cvt_scalef32_pk_f32_fp4 v[100:101], v14, 1.0 op_sel:[1,1,0]
	v_pk_fma_f32 v[100:101], v[100:101], v[114:115], v[102:103] op_sel_hi:[1,0,1]
	v_cvt_scalef32_pk_f32_fp4 v[102:103], v15, 1.0
	v_pk_fma_f32 v[102:103], v[102:103], v[114:115], v[104:105] op_sel_hi:[1,0,1]
	v_cvt_scalef32_pk_f32_fp4 v[104:105], v15, 1.0 op_sel:[1,0,0]
	v_pk_fma_f32 v[104:105], v[104:105], v[114:115], v[106:107] op_sel_hi:[1,0,1]
	v_cvt_scalef32_pk_f32_fp4 v[106:107], v15, 1.0 op_sel:[0,1,0]
	v_pk_fma_f32 v[106:107], v[106:107], v[114:115], v[108:109] op_sel_hi:[1,0,1]
	s_waitcnt vmcnt(6)
	v_cvt_scalef32_pk_f32_fp4 v[108:109], v8, 1.0
	v_pk_fma_f32 v[80:81], v[108:109], v[114:115], v[80:81] op_sel:[0,1,0]
	v_cvt_scalef32_pk_f32_fp4 v[108:109], v8, 1.0 op_sel:[1,0,0]
	v_pk_fma_f32 v[82:83], v[108:109], v[114:115], v[82:83] op_sel:[0,1,0]
	v_cvt_scalef32_pk_f32_fp4 v[108:109], v8, 1.0 op_sel:[0,1,0]
	v_pk_fma_f32 v[84:85], v[108:109], v[114:115], v[84:85] op_sel:[0,1,0]
	v_cvt_scalef32_pk_f32_fp4 v[108:109], v8, 1.0 op_sel:[1,1,0]
	v_pk_fma_f32 v[86:87], v[108:109], v[114:115], v[86:87] op_sel:[0,1,0]
	v_cvt_scalef32_pk_f32_fp4 v[108:109], v9, 1.0
	v_pk_fma_f32 v[88:89], v[108:109], v[114:115], v[88:89] op_sel:[0,1,0]
	v_cvt_scalef32_pk_f32_fp4 v[108:109], v9, 1.0 op_sel:[1,0,0]
	v_pk_fma_f32 v[90:91], v[108:109], v[114:115], v[90:91] op_sel:[0,1,0]
	v_cvt_scalef32_pk_f32_fp4 v[108:109], v9, 1.0 op_sel:[0,1,0]
	v_cvt_scalef32_pk_f32_fp4 v[8:9], v9, 1.0 op_sel:[1,1,0]
	v_pk_fma_f32 v[8:9], v[8:9], v[114:115], v[12:13] op_sel:[0,1,0]
	v_cvt_scalef32_pk_f32_fp4 v[12:13], v10, 1.0
	v_pk_fma_f32 v[12:13], v[12:13], v[114:115], v[94:95] op_sel:[0,1,0]
	v_cvt_scalef32_pk_f32_fp4 v[94:95], v10, 1.0 op_sel:[1,0,0]
	v_pk_fma_f32 v[94:95], v[94:95], v[114:115], v[96:97] op_sel:[0,1,0]
	v_cvt_scalef32_pk_f32_fp4 v[96:97], v10, 1.0 op_sel:[0,1,0]
	v_pk_fma_f32 v[96:97], v[96:97], v[114:115], v[98:99] op_sel:[0,1,0]
	v_cvt_scalef32_pk_f32_fp4 v[98:99], v10, 1.0 op_sel:[1,1,0]
	v_pk_fma_f32 v[98:99], v[98:99], v[114:115], v[100:101] op_sel:[0,1,0]
	v_cvt_scalef32_pk_f32_fp4 v[100:101], v11, 1.0
	v_cvt_scalef32_pk_f32_fp4 v[14:15], v15, 1.0 op_sel:[1,1,0]
	v_pk_fma_f32 v[100:101], v[100:101], v[114:115], v[102:103] op_sel:[0,1,0]
	v_cvt_scalef32_pk_f32_fp4 v[102:103], v11, 1.0 op_sel:[1,0,0]
	v_pk_fma_f32 v[14:15], v[14:15], v[114:115], v[110:111] op_sel_hi:[1,0,1]
	v_pk_fma_f32 v[102:103], v[102:103], v[114:115], v[104:105] op_sel:[0,1,0]
	v_cvt_scalef32_pk_f32_fp4 v[104:105], v11, 1.0 op_sel:[0,1,0]
	v_cvt_scalef32_pk_f32_fp4 v[10:11], v11, 1.0 op_sel:[1,1,0]
	v_pk_fma_f32 v[10:11], v[10:11], v[114:115], v[14:15] op_sel:[0,1,0]
	s_waitcnt vmcnt(5)
	v_cvt_scalef32_pk_f32_fp4 v[14:15], v4, 1.0
	v_pk_fma_f32 v[14:15], v[14:15], v[116:117], v[80:81] op_sel_hi:[1,0,1]
	v_cvt_scalef32_pk_f32_fp4 v[80:81], v4, 1.0 op_sel:[1,0,0]
	v_pk_fma_f32 v[82:83], v[80:81], v[116:117], v[82:83] op_sel_hi:[1,0,1]
	v_cvt_scalef32_pk_f32_fp4 v[80:81], v4, 1.0 op_sel:[0,1,0]
	v_pk_fma_f32 v[84:85], v[80:81], v[116:117], v[84:85] op_sel_hi:[1,0,1]
	v_cvt_scalef32_pk_f32_fp4 v[80:81], v4, 1.0 op_sel:[1,1,0]
	v_pk_fma_f32 v[86:87], v[80:81], v[116:117], v[86:87] op_sel_hi:[1,0,1]
	v_cvt_scalef32_pk_f32_fp4 v[80:81], v5, 1.0
	v_pk_fma_f32 v[88:89], v[80:81], v[116:117], v[88:89] op_sel_hi:[1,0,1]
	v_cvt_scalef32_pk_f32_fp4 v[80:81], v5, 1.0 op_sel:[1,0,0]
	v_pk_fma_f32 v[90:91], v[80:81], v[116:117], v[90:91] op_sel_hi:[1,0,1]
	v_cvt_scalef32_pk_f32_fp4 v[80:81], v5, 1.0 op_sel:[0,1,0]
	v_cvt_scalef32_pk_f32_fp4 v[4:5], v5, 1.0 op_sel:[1,1,0]
	v_pk_fma_f32 v[8:9], v[4:5], v[116:117], v[8:9] op_sel_hi:[1,0,1]
	v_cvt_scalef32_pk_f32_fp4 v[4:5], v6, 1.0
	v_pk_fma_f32 v[12:13], v[4:5], v[116:117], v[12:13] op_sel_hi:[1,0,1]
	v_cvt_scalef32_pk_f32_fp4 v[4:5], v6, 1.0 op_sel:[1,0,0]
	v_pk_fma_f32 v[92:93], v[118:119], v[114:115], v[92:93] op_sel_hi:[1,0,1]
	v_pk_fma_f32 v[104:105], v[104:105], v[114:115], v[106:107] op_sel:[0,1,0]
	v_pk_fma_f32 v[106:107], v[4:5], v[116:117], v[94:95] op_sel_hi:[1,0,1]
	v_cvt_scalef32_pk_f32_fp4 v[4:5], v6, 1.0 op_sel:[0,1,0]
	v_pk_fma_f32 v[92:93], v[108:109], v[114:115], v[92:93] op_sel:[0,1,0]
	v_pk_fma_f32 v[108:109], v[4:5], v[116:117], v[96:97] op_sel_hi:[1,0,1]
	v_cvt_scalef32_pk_f32_fp4 v[4:5], v6, 1.0 op_sel:[1,1,0]
	v_pk_fma_f32 v[110:111], v[4:5], v[116:117], v[98:99] op_sel_hi:[1,0,1]
	v_cvt_scalef32_pk_f32_fp4 v[4:5], v7, 1.0
	v_pk_fma_f32 v[114:115], v[4:5], v[116:117], v[100:101] op_sel_hi:[1,0,1]
	v_cvt_scalef32_pk_f32_fp4 v[4:5], v7, 1.0 op_sel:[1,0,0]
	v_pk_fma_f32 v[118:119], v[4:5], v[116:117], v[102:103] op_sel_hi:[1,0,1]
	v_cvt_scalef32_pk_f32_fp4 v[4:5], v7, 1.0 op_sel:[0,1,0]
	v_pk_fma_f32 v[120:121], v[4:5], v[116:117], v[104:105] op_sel_hi:[1,0,1]
	v_cvt_scalef32_pk_f32_fp4 v[4:5], v7, 1.0 op_sel:[1,1,0]
	v_pk_fma_f32 v[4:5], v[4:5], v[116:117], v[10:11] op_sel_hi:[1,0,1]
	v_mov_b32_e32 v6, v117
	s_waitcnt vmcnt(4)
	v_cvt_scalef32_pk_f32_fp4 v[10:11], v0, 1.0
	v_pk_fma_f32 v[92:93], v[80:81], v[116:117], v[92:93] op_sel_hi:[1,0,1]
	v_pk_fma_f32 v[80:81], v[10:11], v[6:7], v[14:15] op_sel_hi:[1,0,1]
	v_cvt_scalef32_pk_f32_fp4 v[10:11], v0, 1.0 op_sel:[1,0,0]
	v_pk_fma_f32 v[82:83], v[10:11], v[6:7], v[82:83] op_sel_hi:[1,0,1]
	v_cvt_scalef32_pk_f32_fp4 v[10:11], v0, 1.0 op_sel:[0,1,0]
	v_pk_fma_f32 v[84:85], v[10:11], v[6:7], v[84:85] op_sel_hi:[1,0,1]
	v_cvt_scalef32_pk_f32_fp4 v[10:11], v0, 1.0 op_sel:[1,1,0]
	v_pk_fma_f32 v[86:87], v[10:11], v[6:7], v[86:87] op_sel_hi:[1,0,1]
	v_cvt_scalef32_pk_f32_fp4 v[10:11], v1, 1.0
	v_pk_fma_f32 v[88:89], v[10:11], v[6:7], v[88:89] op_sel_hi:[1,0,1]
	v_cvt_scalef32_pk_f32_fp4 v[10:11], v1, 1.0 op_sel:[1,0,0]
	v_pk_fma_f32 v[90:91], v[10:11], v[6:7], v[90:91] op_sel_hi:[1,0,1]
	v_cvt_scalef32_pk_f32_fp4 v[10:11], v1, 1.0 op_sel:[0,1,0]
	v_cvt_scalef32_pk_f32_fp4 v[0:1], v1, 1.0 op_sel:[1,1,0]
	v_pk_fma_f32 v[94:95], v[0:1], v[6:7], v[8:9] op_sel_hi:[1,0,1]
	v_cvt_scalef32_pk_f32_fp4 v[0:1], v2, 1.0
	v_pk_fma_f32 v[96:97], v[0:1], v[6:7], v[12:13] op_sel_hi:[1,0,1]
	v_cvt_scalef32_pk_f32_fp4 v[0:1], v2, 1.0 op_sel:[1,0,0]
	v_pk_fma_f32 v[98:99], v[0:1], v[6:7], v[106:107] op_sel_hi:[1,0,1]
	v_cvt_scalef32_pk_f32_fp4 v[0:1], v2, 1.0 op_sel:[0,1,0]
	v_pk_fma_f32 v[100:101], v[0:1], v[6:7], v[108:109] op_sel_hi:[1,0,1]
	v_cvt_scalef32_pk_f32_fp4 v[0:1], v2, 1.0 op_sel:[1,1,0]
	v_pk_fma_f32 v[102:103], v[0:1], v[6:7], v[110:111] op_sel_hi:[1,0,1]
	v_cvt_scalef32_pk_f32_fp4 v[0:1], v3, 1.0
	v_pk_fma_f32 v[104:105], v[0:1], v[6:7], v[114:115] op_sel_hi:[1,0,1]
	v_cvt_scalef32_pk_f32_fp4 v[0:1], v3, 1.0 op_sel:[1,0,0]
	v_pk_fma_f32 v[106:107], v[0:1], v[6:7], v[118:119] op_sel_hi:[1,0,1]
	v_cvt_scalef32_pk_f32_fp4 v[0:1], v3, 1.0 op_sel:[0,1,0]
	v_pk_fma_f32 v[108:109], v[0:1], v[6:7], v[120:121] op_sel_hi:[1,0,1]
	v_cvt_scalef32_pk_f32_fp4 v[0:1], v3, 1.0 op_sel:[1,1,0]
	v_pk_fma_f32 v[92:93], v[10:11], v[6:7], v[92:93] op_sel_hi:[1,0,1]
	v_pk_fma_f32 v[110:111], v[0:1], v[6:7], v[4:5] op_sel_hi:[1,0,1]
	v_add_u32_e32 v0, s18, v176
	ds_read_b64 v[0:1], v0
	s_waitcnt lgkmcnt(0)
	v_mad_u32_u16 v12, v0, v170, v171
	v_mad_u32_u16 v8, v0, v170, v171 op_sel:[1,0,0,0]
	v_mad_u32_u16 v4, v1, v170, v171
	v_mad_u32_u16 v0, v1, v170, v171 op_sel:[1,0,0,0]
	global_load_dwordx4 v[12:15], v12, s[34:35]
	global_load_dwordx4 v[8:11], v8, s[34:35]
	global_load_dwordx4 v[4:7], v4, s[34:35]
	global_load_dwordx4 v[0:3], v0, s[34:35]
	v_add_u32_e32 v113, s14, v176
	ds_read_b128 v[114:117], v113
	s_waitcnt vmcnt(7)
	v_cvt_scalef32_pk_f32_fp4 v[118:119], v28, 1.0
	s_waitcnt lgkmcnt(0)
	v_pk_fma_f32 v[48:49], v[118:119], v[114:115], v[48:49] op_sel_hi:[1,0,1]
	v_cvt_scalef32_pk_f32_fp4 v[118:119], v28, 1.0 op_sel:[1,0,0]
	v_pk_fma_f32 v[50:51], v[118:119], v[114:115], v[50:51] op_sel_hi:[1,0,1]
	v_cvt_scalef32_pk_f32_fp4 v[118:119], v28, 1.0 op_sel:[0,1,0]
	v_pk_fma_f32 v[52:53], v[118:119], v[114:115], v[52:53] op_sel_hi:[1,0,1]
	v_cvt_scalef32_pk_f32_fp4 v[118:119], v28, 1.0 op_sel:[1,1,0]
	v_pk_fma_f32 v[54:55], v[118:119], v[114:115], v[54:55] op_sel_hi:[1,0,1]
	v_cvt_scalef32_pk_f32_fp4 v[118:119], v29, 1.0
	v_pk_fma_f32 v[56:57], v[118:119], v[114:115], v[56:57] op_sel_hi:[1,0,1]
	v_cvt_scalef32_pk_f32_fp4 v[118:119], v29, 1.0 op_sel:[1,0,0]
	v_pk_fma_f32 v[58:59], v[118:119], v[114:115], v[58:59] op_sel_hi:[1,0,1]
	v_cvt_scalef32_pk_f32_fp4 v[118:119], v29, 1.0 op_sel:[0,1,0]
	v_cvt_scalef32_pk_f32_fp4 v[28:29], v29, 1.0 op_sel:[1,1,0]
	v_pk_fma_f32 v[28:29], v[28:29], v[114:115], v[62:63] op_sel_hi:[1,0,1]
	v_cvt_scalef32_pk_f32_fp4 v[62:63], v30, 1.0
	v_pk_fma_f32 v[62:63], v[62:63], v[114:115], v[64:65] op_sel_hi:[1,0,1]
	v_cvt_scalef32_pk_f32_fp4 v[64:65], v30, 1.0 op_sel:[1,0,0]
	v_pk_fma_f32 v[64:65], v[64:65], v[114:115], v[66:67] op_sel_hi:[1,0,1]
	v_cvt_scalef32_pk_f32_fp4 v[66:67], v30, 1.0 op_sel:[0,1,0]
	v_pk_fma_f32 v[66:67], v[66:67], v[114:115], v[68:69] op_sel_hi:[1,0,1]
	v_cvt_scalef32_pk_f32_fp4 v[68:69], v30, 1.0 op_sel:[1,1,0]
	v_pk_fma_f32 v[68:69], v[68:69], v[114:115], v[70:71] op_sel_hi:[1,0,1]
	v_cvt_scalef32_pk_f32_fp4 v[70:71], v31, 1.0
	v_pk_fma_f32 v[70:71], v[70:71], v[114:115], v[72:73] op_sel_hi:[1,0,1]
	v_cvt_scalef32_pk_f32_fp4 v[72:73], v31, 1.0 op_sel:[1,0,0]
	v_pk_fma_f32 v[72:73], v[72:73], v[114:115], v[74:75] op_sel_hi:[1,0,1]
	v_cvt_scalef32_pk_f32_fp4 v[74:75], v31, 1.0 op_sel:[0,1,0]
	v_pk_fma_f32 v[74:75], v[74:75], v[114:115], v[76:77] op_sel_hi:[1,0,1]
	s_waitcnt vmcnt(6)
	v_cvt_scalef32_pk_f32_fp4 v[76:77], v24, 1.0
	v_pk_fma_f32 v[48:49], v[76:77], v[114:115], v[48:49] op_sel:[0,1,0]
	v_cvt_scalef32_pk_f32_fp4 v[76:77], v24, 1.0 op_sel:[1,0,0]
	v_pk_fma_f32 v[50:51], v[76:77], v[114:115], v[50:51] op_sel:[0,1,0]
	v_cvt_scalef32_pk_f32_fp4 v[76:77], v24, 1.0 op_sel:[0,1,0]
	v_pk_fma_f32 v[52:53], v[76:77], v[114:115], v[52:53] op_sel:[0,1,0]
	v_cvt_scalef32_pk_f32_fp4 v[76:77], v24, 1.0 op_sel:[1,1,0]
	v_pk_fma_f32 v[54:55], v[76:77], v[114:115], v[54:55] op_sel:[0,1,0]
	v_cvt_scalef32_pk_f32_fp4 v[76:77], v25, 1.0
	v_pk_fma_f32 v[56:57], v[76:77], v[114:115], v[56:57] op_sel:[0,1,0]
	v_cvt_scalef32_pk_f32_fp4 v[76:77], v25, 1.0 op_sel:[1,0,0]
	v_pk_fma_f32 v[58:59], v[76:77], v[114:115], v[58:59] op_sel:[0,1,0]
	v_cvt_scalef32_pk_f32_fp4 v[76:77], v25, 1.0 op_sel:[0,1,0]
	v_cvt_scalef32_pk_f32_fp4 v[24:25], v25, 1.0 op_sel:[1,1,0]
	v_pk_fma_f32 v[24:25], v[24:25], v[114:115], v[28:29] op_sel:[0,1,0]
	v_cvt_scalef32_pk_f32_fp4 v[28:29], v26, 1.0
	v_pk_fma_f32 v[28:29], v[28:29], v[114:115], v[62:63] op_sel:[0,1,0]
	v_cvt_scalef32_pk_f32_fp4 v[62:63], v26, 1.0 op_sel:[1,0,0]
	v_pk_fma_f32 v[62:63], v[62:63], v[114:115], v[64:65] op_sel:[0,1,0]
	v_cvt_scalef32_pk_f32_fp4 v[64:65], v26, 1.0 op_sel:[0,1,0]
	v_pk_fma_f32 v[64:65], v[64:65], v[114:115], v[66:67] op_sel:[0,1,0]
	v_cvt_scalef32_pk_f32_fp4 v[66:67], v26, 1.0 op_sel:[1,1,0]
	v_pk_fma_f32 v[66:67], v[66:67], v[114:115], v[68:69] op_sel:[0,1,0]
	v_cvt_scalef32_pk_f32_fp4 v[68:69], v27, 1.0
	v_cvt_scalef32_pk_f32_fp4 v[30:31], v31, 1.0 op_sel:[1,1,0]
	v_pk_fma_f32 v[68:69], v[68:69], v[114:115], v[70:71] op_sel:[0,1,0]
	v_cvt_scalef32_pk_f32_fp4 v[70:71], v27, 1.0 op_sel:[1,0,0]
	v_pk_fma_f32 v[30:31], v[30:31], v[114:115], v[78:79] op_sel_hi:[1,0,1]
	v_pk_fma_f32 v[70:71], v[70:71], v[114:115], v[72:73] op_sel:[0,1,0]
	v_cvt_scalef32_pk_f32_fp4 v[72:73], v27, 1.0 op_sel:[0,1,0]
	v_cvt_scalef32_pk_f32_fp4 v[26:27], v27, 1.0 op_sel:[1,1,0]
	v_pk_fma_f32 v[26:27], v[26:27], v[114:115], v[30:31] op_sel:[0,1,0]
	s_waitcnt vmcnt(5)
	v_cvt_scalef32_pk_f32_fp4 v[30:31], v20, 1.0
	v_pk_fma_f32 v[30:31], v[30:31], v[116:117], v[48:49] op_sel_hi:[1,0,1]
	v_cvt_scalef32_pk_f32_fp4 v[48:49], v20, 1.0 op_sel:[1,0,0]
	v_pk_fma_f32 v[50:51], v[48:49], v[116:117], v[50:51] op_sel_hi:[1,0,1]
	v_cvt_scalef32_pk_f32_fp4 v[48:49], v20, 1.0 op_sel:[0,1,0]
	v_pk_fma_f32 v[52:53], v[48:49], v[116:117], v[52:53] op_sel_hi:[1,0,1]
	v_cvt_scalef32_pk_f32_fp4 v[48:49], v20, 1.0 op_sel:[1,1,0]
	v_pk_fma_f32 v[54:55], v[48:49], v[116:117], v[54:55] op_sel_hi:[1,0,1]
	v_cvt_scalef32_pk_f32_fp4 v[48:49], v21, 1.0
	v_pk_fma_f32 v[56:57], v[48:49], v[116:117], v[56:57] op_sel_hi:[1,0,1]
	v_cvt_scalef32_pk_f32_fp4 v[48:49], v21, 1.0 op_sel:[1,0,0]
	v_pk_fma_f32 v[58:59], v[48:49], v[116:117], v[58:59] op_sel_hi:[1,0,1]
	v_cvt_scalef32_pk_f32_fp4 v[48:49], v21, 1.0 op_sel:[0,1,0]
	v_cvt_scalef32_pk_f32_fp4 v[20:21], v21, 1.0 op_sel:[1,1,0]
	v_pk_fma_f32 v[24:25], v[20:21], v[116:117], v[24:25] op_sel_hi:[1,0,1]
	v_cvt_scalef32_pk_f32_fp4 v[20:21], v22, 1.0
	v_pk_fma_f32 v[28:29], v[20:21], v[116:117], v[28:29] op_sel_hi:[1,0,1]
	v_cvt_scalef32_pk_f32_fp4 v[20:21], v22, 1.0 op_sel:[1,0,0]
	v_pk_fma_f32 v[60:61], v[118:119], v[114:115], v[60:61] op_sel_hi:[1,0,1]
	v_pk_fma_f32 v[72:73], v[72:73], v[114:115], v[74:75] op_sel:[0,1,0]
	v_pk_fma_f32 v[74:75], v[20:21], v[116:117], v[62:63] op_sel_hi:[1,0,1]
	v_cvt_scalef32_pk_f32_fp4 v[20:21], v22, 1.0 op_sel:[0,1,0]
	v_pk_fma_f32 v[60:61], v[76:77], v[114:115], v[60:61] op_sel:[0,1,0]
	v_pk_fma_f32 v[76:77], v[20:21], v[116:117], v[64:65] op_sel_hi:[1,0,1]
	v_cvt_scalef32_pk_f32_fp4 v[20:21], v22, 1.0 op_sel:[1,1,0]
	v_pk_fma_f32 v[78:79], v[20:21], v[116:117], v[66:67] op_sel_hi:[1,0,1]
	v_cvt_scalef32_pk_f32_fp4 v[20:21], v23, 1.0
	v_pk_fma_f32 v[114:115], v[20:21], v[116:117], v[68:69] op_sel_hi:[1,0,1]
	v_cvt_scalef32_pk_f32_fp4 v[20:21], v23, 1.0 op_sel:[1,0,0]
	v_pk_fma_f32 v[118:119], v[20:21], v[116:117], v[70:71] op_sel_hi:[1,0,1]
	v_cvt_scalef32_pk_f32_fp4 v[20:21], v23, 1.0 op_sel:[0,1,0]
	v_pk_fma_f32 v[120:121], v[20:21], v[116:117], v[72:73] op_sel_hi:[1,0,1]
	v_cvt_scalef32_pk_f32_fp4 v[20:21], v23, 1.0 op_sel:[1,1,0]
	v_pk_fma_f32 v[20:21], v[20:21], v[116:117], v[26:27] op_sel_hi:[1,0,1]
	v_mov_b32_e32 v22, v117
	s_waitcnt vmcnt(4)
	v_cvt_scalef32_pk_f32_fp4 v[26:27], v16, 1.0
	v_pk_fma_f32 v[60:61], v[48:49], v[116:117], v[60:61] op_sel_hi:[1,0,1]
	v_pk_fma_f32 v[48:49], v[26:27], v[22:23], v[30:31] op_sel_hi:[1,0,1]
	v_cvt_scalef32_pk_f32_fp4 v[26:27], v16, 1.0 op_sel:[1,0,0]
	v_pk_fma_f32 v[50:51], v[26:27], v[22:23], v[50:51] op_sel_hi:[1,0,1]
	v_cvt_scalef32_pk_f32_fp4 v[26:27], v16, 1.0 op_sel:[0,1,0]
	v_pk_fma_f32 v[52:53], v[26:27], v[22:23], v[52:53] op_sel_hi:[1,0,1]
	v_cvt_scalef32_pk_f32_fp4 v[26:27], v16, 1.0 op_sel:[1,1,0]
	v_pk_fma_f32 v[54:55], v[26:27], v[22:23], v[54:55] op_sel_hi:[1,0,1]
	v_cvt_scalef32_pk_f32_fp4 v[26:27], v17, 1.0
	v_pk_fma_f32 v[56:57], v[26:27], v[22:23], v[56:57] op_sel_hi:[1,0,1]
	v_cvt_scalef32_pk_f32_fp4 v[26:27], v17, 1.0 op_sel:[1,0,0]
	v_pk_fma_f32 v[58:59], v[26:27], v[22:23], v[58:59] op_sel_hi:[1,0,1]
	v_cvt_scalef32_pk_f32_fp4 v[26:27], v17, 1.0 op_sel:[0,1,0]
	v_cvt_scalef32_pk_f32_fp4 v[16:17], v17, 1.0 op_sel:[1,1,0]
	v_pk_fma_f32 v[62:63], v[16:17], v[22:23], v[24:25] op_sel_hi:[1,0,1]
	v_cvt_scalef32_pk_f32_fp4 v[16:17], v18, 1.0
	v_pk_fma_f32 v[64:65], v[16:17], v[22:23], v[28:29] op_sel_hi:[1,0,1]
	v_cvt_scalef32_pk_f32_fp4 v[16:17], v18, 1.0 op_sel:[1,0,0]
	v_pk_fma_f32 v[66:67], v[16:17], v[22:23], v[74:75] op_sel_hi:[1,0,1]
	v_cvt_scalef32_pk_f32_fp4 v[16:17], v18, 1.0 op_sel:[0,1,0]
	v_pk_fma_f32 v[68:69], v[16:17], v[22:23], v[76:77] op_sel_hi:[1,0,1]
	v_cvt_scalef32_pk_f32_fp4 v[16:17], v18, 1.0 op_sel:[1,1,0]
	v_pk_fma_f32 v[70:71], v[16:17], v[22:23], v[78:79] op_sel_hi:[1,0,1]
	v_cvt_scalef32_pk_f32_fp4 v[16:17], v19, 1.0
	v_pk_fma_f32 v[72:73], v[16:17], v[22:23], v[114:115] op_sel_hi:[1,0,1]
	v_cvt_scalef32_pk_f32_fp4 v[16:17], v19, 1.0 op_sel:[1,0,0]
	v_pk_fma_f32 v[74:75], v[16:17], v[22:23], v[118:119] op_sel_hi:[1,0,1]
	v_cvt_scalef32_pk_f32_fp4 v[16:17], v19, 1.0 op_sel:[0,1,0]
	v_pk_fma_f32 v[76:77], v[16:17], v[22:23], v[120:121] op_sel_hi:[1,0,1]
	v_cvt_scalef32_pk_f32_fp4 v[16:17], v19, 1.0 op_sel:[1,1,0]
	v_pk_fma_f32 v[60:61], v[26:27], v[22:23], v[60:61] op_sel_hi:[1,0,1]
	v_pk_fma_f32 v[78:79], v[16:17], v[22:23], v[20:21] op_sel_hi:[1,0,1]
	s_add_i32 s18, s18, 8
	s_add_i32 s16, s16, -1
	s_add_i32 s17, s17, 16
	s_add_i32 s14, s14, 16
	s_add_i32 s15, s15, 8
	s_cmp_lg_u32 s16, 0
	s_cbranch_scc1 .LBB0_808
	v_lshl_add_u32 v119, s13, 8, v177
	ds_read_b64 v[24:25], v119 offset:2808
	v_mov_b32_e32 v17, v137
	s_waitcnt lgkmcnt(0)
	v_lshlrev_b32_sdwa v136, v188, v24 dst_sel:DWORD dst_unused:UNUSED_PAD src0_sel:DWORD src1_sel:WORD_0
	v_lshlrev_b32_sdwa v16, v188, v24 dst_sel:DWORD dst_unused:UNUSED_PAD src0_sel:DWORD src1_sel:WORD_1
	v_lshl_add_u64 v[18:19], v[32:33], 0, v[136:137]
	v_lshlrev_b32_sdwa v24, v188, v25 dst_sel:DWORD dst_unused:UNUSED_PAD src0_sel:DWORD src1_sel:WORD_1
	v_lshlrev_b32_sdwa v136, v188, v25 dst_sel:DWORD dst_unused:UNUSED_PAD src0_sel:DWORD src1_sel:WORD_0
	v_mov_b32_e32 v25, v137
	v_lshl_add_u64 v[20:21], v[32:33], 0, v[16:17]
	v_lshl_add_u64 v[26:27], v[32:33], 0, v[136:137]
	v_lshl_add_u64 v[28:29], v[32:33], 0, v[24:25]
	global_load_dwordx4 v[16:19], v[18:19], off
	s_nop 0
	global_load_dwordx4 v[20:23], v[20:21], off
	s_nop 0
	global_load_dwordx4 v[24:27], v[26:27], off
	s_nop 0
	global_load_dwordx4 v[28:31], v[28:29], off
	v_lshl_add_u32 v112, s8, 8, v112
	ds_read_b128 v[112:115], v112 offset:5104
	s_waitcnt vmcnt(7)
	v_cvt_scalef32_pk_f32_fp4 v[124:125], v15, 1.0 op_sel:[1,1,0]
	s_waitcnt vmcnt(6)
	v_cvt_scalef32_pk_f32_fp4 v[122:123], v11, 1.0 op_sel:[1,1,0]
	s_waitcnt lgkmcnt(0)
	v_pk_fma_f32 v[110:111], v[124:125], v[112:113], v[110:111] op_sel_hi:[1,0,1]
	v_cvt_scalef32_pk_f32_fp4 v[124:125], v15, 1.0 op_sel:[0,1,0]
	s_waitcnt vmcnt(5)
	v_cvt_scalef32_pk_f32_fp4 v[120:121], v7, 1.0 op_sel:[1,1,0]
	v_pk_fma_f32 v[110:111], v[122:123], v[112:113], v[110:111] op_sel:[0,1,0]
	v_cvt_scalef32_pk_f32_fp4 v[122:123], v11, 1.0 op_sel:[0,1,0]
	v_pk_fma_f32 v[108:109], v[124:125], v[112:113], v[108:109] op_sel_hi:[1,0,1]
	v_cvt_scalef32_pk_f32_fp4 v[124:125], v15, 1.0 op_sel:[1,0,0]
	s_waitcnt vmcnt(4)
	v_cvt_scalef32_pk_f32_fp4 v[116:117], v3, 1.0 op_sel:[1,1,0]
	v_mov_b32_e32 v118, v115
	v_pk_fma_f32 v[110:111], v[120:121], v[114:115], v[110:111] op_sel_hi:[1,0,1]
	v_cvt_scalef32_pk_f32_fp4 v[120:121], v7, 1.0 op_sel:[0,1,0]
	v_pk_fma_f32 v[108:109], v[122:123], v[112:113], v[108:109] op_sel:[0,1,0]
	v_cvt_scalef32_pk_f32_fp4 v[122:123], v11, 1.0 op_sel:[1,0,0]
	v_pk_fma_f32 v[106:107], v[124:125], v[112:113], v[106:107] op_sel_hi:[1,0,1]
	v_cvt_scalef32_pk_f32_fp4 v[124:125], v15, 1.0
	v_pk_fma_f32 v[110:111], v[116:117], v[118:119], v[110:111] op_sel_hi:[1,0,1]
	v_cvt_scalef32_pk_f32_fp4 v[116:117], v3, 1.0 op_sel:[0,1,0]
	v_pk_fma_f32 v[108:109], v[120:121], v[114:115], v[108:109] op_sel_hi:[1,0,1]
	v_cvt_scalef32_pk_f32_fp4 v[120:121], v7, 1.0 op_sel:[1,0,0]
	v_pk_fma_f32 v[106:107], v[122:123], v[112:113], v[106:107] op_sel:[0,1,0]
	v_cvt_scalef32_pk_f32_fp4 v[122:123], v11, 1.0
	v_pk_fma_f32 v[104:105], v[124:125], v[112:113], v[104:105] op_sel_hi:[1,0,1]
	v_cvt_scalef32_pk_f32_fp4 v[124:125], v14, 1.0 op_sel:[1,1,0]
	v_pk_fma_f32 v[108:109], v[116:117], v[118:119], v[108:109] op_sel_hi:[1,0,1]
	v_cvt_scalef32_pk_f32_fp4 v[116:117], v3, 1.0 op_sel:[1,0,0]
	v_pk_fma_f32 v[106:107], v[120:121], v[114:115], v[106:107] op_sel_hi:[1,0,1]
	v_cvt_scalef32_pk_f32_fp4 v[120:121], v7, 1.0
	v_pk_fma_f32 v[104:105], v[122:123], v[112:113], v[104:105] op_sel:[0,1,0]
	v_cvt_scalef32_pk_f32_fp4 v[122:123], v10, 1.0 op_sel:[1,1,0]
	v_pk_fma_f32 v[102:103], v[124:125], v[112:113], v[102:103] op_sel_hi:[1,0,1]
	v_pk_fma_f32 v[106:107], v[116:117], v[118:119], v[106:107] op_sel_hi:[1,0,1]
	v_cvt_scalef32_pk_f32_fp4 v[116:117], v3, 1.0
	v_pk_fma_f32 v[104:105], v[120:121], v[114:115], v[104:105] op_sel_hi:[1,0,1]
	v_cvt_scalef32_pk_f32_fp4 v[120:121], v6, 1.0 op_sel:[1,1,0]
	v_pk_fma_f32 v[102:103], v[122:123], v[112:113], v[102:103] op_sel:[0,1,0]
	v_cvt_scalef32_pk_f32_fp4 v[122:123], v14, 1.0 op_sel:[0,1,0]
	v_pk_fma_f32 v[104:105], v[116:117], v[118:119], v[104:105] op_sel_hi:[1,0,1]
	v_cvt_scalef32_pk_f32_fp4 v[116:117], v2, 1.0 op_sel:[1,1,0]
	v_pk_fma_f32 v[102:103], v[120:121], v[114:115], v[102:103] op_sel_hi:[1,0,1]
	v_cvt_scalef32_pk_f32_fp4 v[120:121], v10, 1.0 op_sel:[0,1,0]
	v_pk_fma_f32 v[100:101], v[122:123], v[112:113], v[100:101] op_sel_hi:[1,0,1]
	v_pk_fma_f32 v[206:207], v[116:117], v[118:119], v[102:103] op_sel_hi:[1,0,1]
	v_cvt_scalef32_pk_f32_fp4 v[116:117], v6, 1.0 op_sel:[0,1,0]
	v_pk_fma_f32 v[100:101], v[120:121], v[112:113], v[100:101] op_sel:[0,1,0]
	v_cvt_scalef32_pk_f32_fp4 v[120:121], v14, 1.0 op_sel:[1,0,0]
	v_cvt_scalef32_pk_f32_fp4 v[14:15], v14, 1.0
	v_cvt_scalef32_pk_f32_fp4 v[102:103], v2, 1.0 op_sel:[0,1,0]
	v_pk_fma_f32 v[100:101], v[116:117], v[114:115], v[100:101] op_sel_hi:[1,0,1]
	v_cvt_scalef32_pk_f32_fp4 v[116:117], v10, 1.0 op_sel:[1,0,0]
	v_cvt_scalef32_pk_f32_fp4 v[10:11], v10, 1.0
	v_pk_fma_f32 v[14:15], v[14:15], v[112:113], v[96:97] op_sel_hi:[1,0,1]
	v_pk_fma_f32 v[208:209], v[102:103], v[118:119], v[100:101] op_sel_hi:[1,0,1]
	v_cvt_scalef32_pk_f32_fp4 v[102:103], v6, 1.0 op_sel:[1,0,0]
	v_cvt_scalef32_pk_f32_fp4 v[6:7], v6, 1.0
	v_pk_fma_f32 v[10:11], v[10:11], v[112:113], v[14:15] op_sel:[0,1,0]
	v_cvt_scalef32_pk_f32_fp4 v[14:15], v13, 1.0 op_sel:[1,1,0]
	v_cvt_scalef32_pk_f32_fp4 v[100:101], v2, 1.0 op_sel:[1,0,0]
	v_cvt_scalef32_pk_f32_fp4 v[2:3], v2, 1.0
	v_pk_fma_f32 v[6:7], v[6:7], v[114:115], v[10:11] op_sel_hi:[1,0,1]
	v_cvt_scalef32_pk_f32_fp4 v[10:11], v9, 1.0 op_sel:[1,1,0]
	v_pk_fma_f32 v[14:15], v[14:15], v[112:113], v[94:95] op_sel_hi:[1,0,1]
	v_pk_fma_f32 v[212:213], v[2:3], v[118:119], v[6:7] op_sel_hi:[1,0,1]
	v_cvt_scalef32_pk_f32_fp4 v[6:7], v5, 1.0 op_sel:[1,1,0]
	v_pk_fma_f32 v[10:11], v[10:11], v[112:113], v[14:15] op_sel:[0,1,0]
	v_cvt_scalef32_pk_f32_fp4 v[14:15], v13, 1.0 op_sel:[0,1,0]
	v_cvt_scalef32_pk_f32_fp4 v[2:3], v1, 1.0 op_sel:[1,1,0]
	v_pk_fma_f32 v[6:7], v[6:7], v[114:115], v[10:11] op_sel_hi:[1,0,1]
	v_cvt_scalef32_pk_f32_fp4 v[10:11], v9, 1.0 op_sel:[0,1,0]
	v_pk_fma_f32 v[14:15], v[14:15], v[112:113], v[92:93] op_sel_hi:[1,0,1]
	v_pk_fma_f32 v[214:215], v[2:3], v[118:119], v[6:7] op_sel_hi:[1,0,1]
	v_cvt_scalef32_pk_f32_fp4 v[6:7], v5, 1.0 op_sel:[0,1,0]
	v_pk_fma_f32 v[10:11], v[10:11], v[112:113], v[14:15] op_sel:[0,1,0]
	v_cvt_scalef32_pk_f32_fp4 v[14:15], v13, 1.0 op_sel:[1,0,0]
	v_cvt_scalef32_pk_f32_fp4 v[2:3], v1, 1.0 op_sel:[0,1,0]
	v_pk_fma_f32 v[6:7], v[6:7], v[114:115], v[10:11] op_sel_hi:[1,0,1]
	v_cvt_scalef32_pk_f32_fp4 v[10:11], v9, 1.0 op_sel:[1,0,0]
	v_pk_fma_f32 v[14:15], v[14:15], v[112:113], v[90:91] op_sel_hi:[1,0,1]
	v_pk_fma_f32 v[216:217], v[2:3], v[118:119], v[6:7] op_sel_hi:[1,0,1]
	v_cvt_scalef32_pk_f32_fp4 v[6:7], v5, 1.0 op_sel:[1,0,0]
	v_pk_fma_f32 v[10:11], v[10:11], v[112:113], v[14:15] op_sel:[0,1,0]
	v_cvt_scalef32_pk_f32_fp4 v[14:15], v13, 1.0
	v_cvt_scalef32_pk_f32_fp4 v[2:3], v1, 1.0 op_sel:[1,0,0]
	v_pk_fma_f32 v[6:7], v[6:7], v[114:115], v[10:11] op_sel_hi:[1,0,1]
	v_cvt_scalef32_pk_f32_fp4 v[10:11], v9, 1.0
	v_pk_fma_f32 v[14:15], v[14:15], v[112:113], v[88:89] op_sel_hi:[1,0,1]
	v_pk_fma_f32 v[218:219], v[2:3], v[118:119], v[6:7] op_sel_hi:[1,0,1]
	v_cvt_scalef32_pk_f32_fp4 v[6:7], v5, 1.0
	v_pk_fma_f32 v[10:11], v[10:11], v[112:113], v[14:15] op_sel:[0,1,0]
	v_cvt_scalef32_pk_f32_fp4 v[14:15], v12, 1.0 op_sel:[1,1,0]
	v_cvt_scalef32_pk_f32_fp4 v[2:3], v1, 1.0
	v_pk_fma_f32 v[6:7], v[6:7], v[114:115], v[10:11] op_sel_hi:[1,0,1]
	v_cvt_scalef32_pk_f32_fp4 v[10:11], v8, 1.0 op_sel:[1,1,0]
	v_pk_fma_f32 v[14:15], v[14:15], v[112:113], v[86:87] op_sel_hi:[1,0,1]
	v_pk_fma_f32 v[220:221], v[2:3], v[118:119], v[6:7] op_sel_hi:[1,0,1]
	v_cvt_scalef32_pk_f32_fp4 v[6:7], v4, 1.0 op_sel:[1,1,0]
	v_pk_fma_f32 v[10:11], v[10:11], v[112:113], v[14:15] op_sel:[0,1,0]
	v_cvt_scalef32_pk_f32_fp4 v[14:15], v12, 1.0 op_sel:[0,1,0]
	v_cvt_scalef32_pk_f32_fp4 v[2:3], v0, 1.0 op_sel:[1,1,0]
	v_pk_fma_f32 v[6:7], v[6:7], v[114:115], v[10:11] op_sel_hi:[1,0,1]
	v_cvt_scalef32_pk_f32_fp4 v[10:11], v8, 1.0 op_sel:[0,1,0]
	v_pk_fma_f32 v[14:15], v[14:15], v[112:113], v[84:85] op_sel_hi:[1,0,1]
	v_pk_fma_f32 v[222:223], v[2:3], v[118:119], v[6:7] op_sel_hi:[1,0,1]
	v_cvt_scalef32_pk_f32_fp4 v[6:7], v4, 1.0 op_sel:[0,1,0]
	v_pk_fma_f32 v[10:11], v[10:11], v[112:113], v[14:15] op_sel:[0,1,0]
	v_cvt_scalef32_pk_f32_fp4 v[14:15], v12, 1.0 op_sel:[1,0,0]
	v_cvt_scalef32_pk_f32_fp4 v[2:3], v0, 1.0 op_sel:[0,1,0]
	v_pk_fma_f32 v[6:7], v[6:7], v[114:115], v[10:11] op_sel_hi:[1,0,1]
	v_cvt_scalef32_pk_f32_fp4 v[10:11], v8, 1.0 op_sel:[1,0,0]
	v_pk_fma_f32 v[14:15], v[14:15], v[112:113], v[82:83] op_sel_hi:[1,0,1]
	v_pk_fma_f32 v[224:225], v[2:3], v[118:119], v[6:7] op_sel_hi:[1,0,1]
	v_cvt_scalef32_pk_f32_fp4 v[6:7], v4, 1.0 op_sel:[1,0,0]
	v_pk_fma_f32 v[10:11], v[10:11], v[112:113], v[14:15] op_sel:[0,1,0]
	v_cvt_scalef32_pk_f32_fp4 v[2:3], v0, 1.0 op_sel:[1,0,0]
	v_pk_fma_f32 v[6:7], v[6:7], v[114:115], v[10:11] op_sel_hi:[1,0,1]
	v_pk_fma_f32 v[98:99], v[120:121], v[112:113], v[98:99] op_sel_hi:[1,0,1]
	v_pk_fma_f32 v[226:227], v[2:3], v[118:119], v[6:7] op_sel_hi:[1,0,1]
	v_cvt_scalef32_pk_f32_fp4 v[6:7], v12, 1.0
	v_cvt_scalef32_pk_f32_fp4 v[2:3], v4, 1.0
	v_cvt_scalef32_pk_f32_fp4 v[4:5], v8, 1.0
	v_pk_fma_f32 v[6:7], v[6:7], v[112:113], v[80:81] op_sel_hi:[1,0,1]
	v_pk_fma_f32 v[98:99], v[116:117], v[112:113], v[98:99] op_sel:[0,1,0]
	v_pk_fma_f32 v[4:5], v[4:5], v[112:113], v[6:7] op_sel:[0,1,0]
	v_pk_fma_f32 v[98:99], v[102:103], v[114:115], v[98:99] op_sel_hi:[1,0,1]
	v_cvt_scalef32_pk_f32_fp4 v[0:1], v0, 1.0
	v_pk_fma_f32 v[2:3], v[2:3], v[114:115], v[4:5] op_sel_hi:[1,0,1]
	v_pk_fma_f32 v[210:211], v[100:101], v[118:119], v[98:99] op_sel_hi:[1,0,1]
	v_pk_fma_f32 v[228:229], v[0:1], v[118:119], v[2:3] op_sel_hi:[1,0,1]
	v_add_u32_e32 v0, s12, v119
	ds_read_b128 v[0:3], v0 offset:5104
	s_mul_i32 s12, s8, s33
	v_add_u32_e32 v4, s12, v172
	v_ashrrev_i32_e32 v6, 11, v4
	v_mul_i32_i24_e32 v6, 0x3000, v6
	v_ashrrev_i32_e32 v7, 31, v6
	v_lshl_add_u64 v[6:7], v[6:7], 2, s[72:73]
	v_lshl_add_u64 v[6:7], v[34:35], 2, v[6:7]
	v_add_co_u32_e32 v198, vcc, s80, v6
	v_ashrrev_i32_e32 v5, 31, v4
	s_nop 0
	v_addc_co_u32_e32 v199, vcc, 0, v7, vcc
	v_lshlrev_b64 v[4:5], 13, v[4:5]
	global_load_dwordx4 v[8:11], v[198:199], off offset:-4096
	v_lshl_add_u64 v[92:93], v[6:7], 0, s[54:55]
	v_lshl_add_u64 v[6:7], v[46:47], 0, v[4:5]
	global_load_dwordx4 v[12:15], v[6:7], off nt
	global_load_dwordx4 v[80:83], v[6:7], off offset:1024 nt
	global_load_dwordx4 v[84:87], v[92:93], off offset:1024
	global_load_dwordx4 v[88:91], v[92:93], off offset:2048
	s_nop 0
	global_load_dwordx4 v[92:95], v[92:93], off offset:3072
	s_nop 0
	global_load_dwordx4 v[96:99], v[6:7], off offset:2048 nt
	global_load_dwordx4 v[100:103], v[6:7], off offset:3072 nt
	global_load_dwordx4 v[112:115], v[198:199], off
	v_add_co_u32_e32 v4, vcc, s63, v6
	v_mov_b32_e32 v230, v228
	s_nop 0
	v_addc_co_u32_e32 v5, vcc, 0, v7, vcc
	global_load_dwordx4 v[116:119], v[4:5], off nt
	global_load_dwordx4 v[120:123], v[4:5], off offset:1024 nt
	global_load_dwordx4 v[124:127], v[198:199], off offset:1024
	global_load_dwordx4 v[128:131], v[198:199], off offset:2048
	global_load_dwordx4 v[132:135], v[4:5], off offset:2048 nt
	global_load_dwordx4 v[194:197], v[4:5], off offset:3072 nt
	s_nop 0
	global_load_dwordx4 v[198:201], v[198:199], off offset:3072
	s_nop 0
	global_load_dwordx4 v[202:205], v[36:37], off
	v_mov_b32_e32 v231, v226
	v_mov_b32_e32 v232, v224
	v_mov_b32_e32 v233, v222
	v_mov_b32_e32 v226, v229
	v_mov_b32_e32 v222, v225
	v_mov_b32_e32 v229, v214
	v_mov_b32_e32 v214, v217
	v_mov_b32_e32 v224, v220
	v_mov_b32_e32 v225, v218
	v_mov_b32_e32 v218, v221
	v_mov_b32_e32 v220, v208
	v_mov_b32_e32 v221, v206
	v_mov_b32_e32 v206, v209
	v_mov_b32_e32 v208, v104
	v_mov_b32_e32 v209, v106
	v_mov_b32_e32 v106, v105
	v_mov_b32_e32 v228, v216
	v_mov_b32_e32 v216, v212
	v_mov_b32_e32 v217, v210
	v_mov_b32_e32 v210, v213
	v_mov_b32_e32 v212, v108
	v_mov_b32_e32 v213, v110
	v_mov_b32_e32 v110, v109
	s_waitcnt vmcnt(15)
	v_pk_fma_f32 v[8:9], v[230:231], v[8:9], v[12:13]
	v_pk_fma_f32 v[10:11], v[232:233], v[10:11], v[14:15]
	s_waitcnt vmcnt(13)
	v_pk_fma_f32 v[14:15], v[222:223], v[86:87], v[82:83]
	s_waitcnt vmcnt(9)
	v_pk_fma_f32 v[86:87], v[214:215], v[94:95], v[102:103]
	v_pk_mul_f32 v[102:103], v[8:9], v[8:9]
	v_pk_mul_f32 v[104:105], v[10:11], v[10:11]
	v_add_f32_e32 v102, v102, v103
	v_pk_fma_f32 v[12:13], v[226:227], v[84:85], v[80:81]
	v_add_f32_e32 v102, v104, v102
	v_pk_fma_f32 v[84:85], v[218:219], v[92:93], v[100:101]
	s_waitcnt vmcnt(1)
	v_pk_fma_f32 v[100:101], v[106:107], v[198:199], v[194:195]
	v_pk_mul_f32 v[106:107], v[12:13], v[12:13]
	v_add_f32_e32 v102, v105, v102
	v_add_f32_e32 v102, v106, v102
	v_pk_mul_f32 v[108:109], v[14:15], v[14:15]
	v_add_f32_e32 v102, v107, v102
	v_pk_fma_f32 v[80:81], v[224:225], v[88:89], v[96:97]
	v_add_f32_e32 v102, v108, v102
	v_pk_fma_f32 v[88:89], v[216:217], v[112:113], v[116:117]
	v_pk_mul_f32 v[112:113], v[80:81], v[80:81]
	v_add_f32_e32 v102, v109, v102
	v_pk_fma_f32 v[82:83], v[228:229], v[90:91], v[98:99]
	v_add_f32_e32 v102, v112, v102
	v_pk_fma_f32 v[90:91], v[220:221], v[114:115], v[118:119]
	v_pk_mul_f32 v[114:115], v[82:83], v[82:83]
	v_add_f32_e32 v102, v113, v102
	v_add_f32_e32 v102, v114, v102
	v_pk_mul_f32 v[116:117], v[84:85], v[84:85]
	v_add_f32_e32 v102, v115, v102
	v_add_f32_e32 v102, v116, v102
	v_pk_mul_f32 v[118:119], v[86:87], v[86:87]
	v_add_f32_e32 v102, v117, v102
	v_add_f32_e32 v102, v118, v102
	v_pk_fma_f32 v[92:93], v[210:211], v[124:125], v[120:121]
	v_pk_mul_f32 v[120:121], v[88:89], v[88:89]
	v_add_f32_e32 v102, v119, v102
	v_add_f32_e32 v102, v120, v102
	v_pk_fma_f32 v[94:95], v[206:207], v[126:127], v[122:123]
	v_pk_mul_f32 v[122:123], v[90:91], v[90:91]
	v_add_f32_e32 v102, v121, v102
	v_add_f32_e32 v102, v122, v102
	v_pk_mul_f32 v[124:125], v[92:93], v[92:93]
	v_add_f32_e32 v102, v123, v102
	v_add_f32_e32 v102, v124, v102
	v_pk_mul_f32 v[126:127], v[94:95], v[94:95]
	v_add_f32_e32 v102, v125, v102
	v_pk_fma_f32 v[96:97], v[208:209], v[128:129], v[132:133]
	v_add_f32_e32 v102, v126, v102
	v_pk_mul_f32 v[128:129], v[96:97], v[96:97]
	v_add_f32_e32 v102, v127, v102
	v_pk_fma_f32 v[98:99], v[212:213], v[130:131], v[134:135]
	v_add_f32_e32 v102, v128, v102
	v_pk_mul_f32 v[130:131], v[98:99], v[98:99]
	v_add_f32_e32 v102, v129, v102
	v_add_f32_e32 v102, v130, v102
	v_pk_mul_f32 v[132:133], v[100:101], v[100:101]
	v_add_f32_e32 v102, v131, v102
	v_pk_fma_f32 v[110:111], v[110:111], v[200:201], v[196:197]
	v_add_f32_e32 v102, v132, v102
	v_pk_mul_f32 v[134:135], v[110:111], v[110:111]
	v_add_f32_e32 v102, v133, v102
	v_add_f32_e32 v102, v134, v102
	v_add_f32_e32 v102, v135, v102
	s_nop 1
	v_add_f32_dpp v102, v102, v102 quad_perm:[1,0,3,2] row_mask:0xf bank_mask:0xf bound_ctrl:1
	s_nop 1
	v_add_f32_dpp v102, v102, v102 quad_perm:[2,3,0,1] row_mask:0xf bank_mask:0xf bound_ctrl:1
	s_nop 1
	v_add_f32_dpp v102, v102, v102 row_half_mirror row_mask:0xf bank_mask:0xf bound_ctrl:1
	s_nop 1
	v_add_f32_dpp v102, v102, v102 row_mirror row_mask:0xf bank_mask:0xf bound_ctrl:1
	v_mov_b32_e32 v103, v102
	s_nop 1
	v_permlane16_swap_b32_e32 v102, v103
	v_add_f32_e32 v102, v102, v103
	v_mov_b32_e32 v103, v102
	s_nop 1
	v_permlane32_swap_b32_e32 v102, v103
	v_add_f32_e32 v102, v102, v103
	v_fmamk_f32 v102, v102, 0x3a000000, v184
	v_mul_f32_e32 v103, 0x4b800000, v102
	v_cmp_gt_f32_e32 vcc, s64, v102
	s_nop 1
	v_cndmask_b32_e32 v102, v102, v103, vcc
	v_rsq_f32_e32 v102, v102
	s_nop 0
	v_mul_f32_e32 v103, 0x45800000, v102
	v_cndmask_b32_e32 v102, v102, v103, vcc
	v_pk_mul_f32 v[8:9], v[8:9], v[102:103] op_sel_hi:[1,0]
	v_pk_mul_f32 v[10:11], v[10:11], v[102:103] op_sel_hi:[1,0]
	s_waitcnt vmcnt(0)
	v_pk_mul_f32 v[8:9], v[202:203], v[8:9]
	v_pk_mul_f32 v[10:11], v[204:205], v[10:11]
	global_store_dwordx4 v[6:7], v[8:11], off nt
	global_load_dwordx4 v[8:11], v[36:37], off offset:1024
	v_pk_mul_f32 v[14:15], v[14:15], v[102:103] op_sel_hi:[1,0]
	v_pk_mul_f32 v[12:13], v[12:13], v[102:103] op_sel_hi:[1,0]
	s_andn2_b64 vcc, exec, s[6:7]
	s_waitcnt vmcnt(0)
	v_pk_mul_f32 v[8:9], v[8:9], v[12:13]
	v_pk_mul_f32 v[10:11], v[10:11], v[14:15]
	global_store_dwordx4 v[6:7], v[8:11], off offset:1024 nt
	global_load_dwordx4 v[8:11], v[36:37], off offset:2048
	v_pk_mul_f32 v[12:13], v[82:83], v[102:103] op_sel_hi:[1,0]
	v_pk_mul_f32 v[14:15], v[80:81], v[102:103] op_sel_hi:[1,0]
	s_waitcnt vmcnt(0)
	v_pk_mul_f32 v[10:11], v[10:11], v[12:13]
	v_pk_mul_f32 v[8:9], v[8:9], v[14:15]
	global_store_dwordx4 v[6:7], v[8:11], off offset:2048 nt
	global_load_dwordx4 v[8:11], v[36:37], off offset:3072
	v_pk_mul_f32 v[12:13], v[86:87], v[102:103] op_sel_hi:[1,0]
	v_pk_mul_f32 v[14:15], v[84:85], v[102:103] op_sel_hi:[1,0]
	s_waitcnt vmcnt(0)
	v_pk_mul_f32 v[10:11], v[10:11], v[12:13]
	v_pk_mul_f32 v[8:9], v[8:9], v[14:15]
	global_store_dwordx4 v[6:7], v[8:11], off offset:3072 nt
	global_load_dwordx4 v[6:9], v[38:39], off
	v_pk_mul_f32 v[12:13], v[88:89], v[102:103] op_sel_hi:[1,0]
	v_pk_mul_f32 v[10:11], v[90:91], v[102:103] op_sel_hi:[1,0]
	s_waitcnt vmcnt(0)
	v_pk_mul_f32 v[6:7], v[6:7], v[12:13]
	v_pk_mul_f32 v[8:9], v[8:9], v[10:11]
	global_store_dwordx4 v[4:5], v[6:9], off nt
	global_load_dwordx4 v[6:9], v[40:41], off
	v_pk_mul_f32 v[10:11], v[94:95], v[102:103] op_sel_hi:[1,0]
	v_pk_mul_f32 v[12:13], v[92:93], v[102:103] op_sel_hi:[1,0]
	s_waitcnt vmcnt(0)
	v_pk_mul_f32 v[8:9], v[10:11], v[8:9]
	v_pk_mul_f32 v[6:7], v[12:13], v[6:7]
	global_store_dwordx4 v[4:5], v[6:9], off offset:1024 nt
	global_load_dwordx4 v[6:9], v[42:43], off
	v_pk_mul_f32 v[10:11], v[98:99], v[102:103] op_sel_hi:[1,0]
	v_pk_mul_f32 v[12:13], v[96:97], v[102:103] op_sel_hi:[1,0]
	s_waitcnt vmcnt(0)
	v_pk_mul_f32 v[8:9], v[10:11], v[8:9]
	v_pk_mul_f32 v[6:7], v[12:13], v[6:7]
	global_store_dwordx4 v[4:5], v[6:9], off offset:2048 nt
	global_load_dwordx4 v[6:9], v[44:45], off
	v_pk_mul_f32 v[10:11], v[110:111], v[102:103] op_sel_hi:[1,0]
	v_pk_mul_f32 v[12:13], v[100:101], v[102:103] op_sel_hi:[1,0]
	s_waitcnt vmcnt(0)
	v_pk_mul_f32 v[8:9], v[10:11], v[8:9]
	v_pk_mul_f32 v[6:7], v[12:13], v[6:7]
	global_store_dwordx4 v[4:5], v[6:9], off offset:3072 nt
	s_cbranch_vccnz .LBB0_806
	v_cvt_scalef32_pk_f32_fp4 v[10:11], v19, 1.0 op_sel:[1,1,0]
	v_cvt_scalef32_pk_f32_fp4 v[8:9], v23, 1.0 op_sel:[1,1,0]
	s_waitcnt lgkmcnt(0)
	v_pk_fma_f32 v[10:11], v[10:11], v[0:1], v[78:79] op_sel_hi:[1,0,1]
	v_cvt_scalef32_pk_f32_fp4 v[12:13], v19, 1.0 op_sel:[0,1,0]
	v_cvt_scalef32_pk_f32_fp4 v[6:7], v27, 1.0 op_sel:[1,1,0]
	v_pk_fma_f32 v[8:9], v[8:9], v[0:1], v[10:11] op_sel:[0,1,0]
	v_cvt_scalef32_pk_f32_fp4 v[10:11], v23, 1.0 op_sel:[0,1,0]
	v_pk_fma_f32 v[12:13], v[12:13], v[0:1], v[76:77] op_sel_hi:[1,0,1]
	v_cvt_scalef32_pk_f32_fp4 v[14:15], v19, 1.0 op_sel:[1,0,0]
	v_cvt_scalef32_pk_f32_fp4 v[4:5], v31, 1.0 op_sel:[1,1,0]
	v_mov_b32_e32 v124, v3
	v_pk_fma_f32 v[6:7], v[6:7], v[2:3], v[8:9] op_sel_hi:[1,0,1]
	v_cvt_scalef32_pk_f32_fp4 v[8:9], v27, 1.0 op_sel:[0,1,0]
	v_pk_fma_f32 v[10:11], v[10:11], v[0:1], v[12:13] op_sel:[0,1,0]
	v_cvt_scalef32_pk_f32_fp4 v[12:13], v23, 1.0 op_sel:[1,0,0]
	v_pk_fma_f32 v[14:15], v[14:15], v[0:1], v[74:75] op_sel_hi:[1,0,1]
	v_cvt_scalef32_pk_f32_fp4 v[74:75], v19, 1.0
	v_pk_fma_f32 v[4:5], v[4:5], v[124:125], v[6:7] op_sel_hi:[1,0,1]
	v_cvt_scalef32_pk_f32_fp4 v[6:7], v31, 1.0 op_sel:[0,1,0]
	v_pk_fma_f32 v[8:9], v[8:9], v[2:3], v[10:11] op_sel_hi:[1,0,1]
	v_cvt_scalef32_pk_f32_fp4 v[10:11], v27, 1.0 op_sel:[1,0,0]
	v_pk_fma_f32 v[12:13], v[12:13], v[0:1], v[14:15] op_sel:[0,1,0]
	v_cvt_scalef32_pk_f32_fp4 v[14:15], v23, 1.0
	v_pk_fma_f32 v[72:73], v[74:75], v[0:1], v[72:73] op_sel_hi:[1,0,1]
	v_cvt_scalef32_pk_f32_fp4 v[74:75], v18, 1.0 op_sel:[1,1,0]
	v_pk_fma_f32 v[6:7], v[6:7], v[124:125], v[8:9] op_sel_hi:[1,0,1]
	v_cvt_scalef32_pk_f32_fp4 v[8:9], v31, 1.0 op_sel:[1,0,0]
	v_pk_fma_f32 v[10:11], v[10:11], v[2:3], v[12:13] op_sel_hi:[1,0,1]
	v_cvt_scalef32_pk_f32_fp4 v[12:13], v27, 1.0
	v_pk_fma_f32 v[14:15], v[14:15], v[0:1], v[72:73] op_sel:[0,1,0]
	v_cvt_scalef32_pk_f32_fp4 v[72:73], v22, 1.0 op_sel:[1,1,0]
	v_pk_fma_f32 v[70:71], v[74:75], v[0:1], v[70:71] op_sel_hi:[1,0,1]
	v_pk_fma_f32 v[10:11], v[8:9], v[124:125], v[10:11] op_sel_hi:[1,0,1]
	v_cvt_scalef32_pk_f32_fp4 v[8:9], v31, 1.0
	v_pk_fma_f32 v[12:13], v[12:13], v[2:3], v[14:15] op_sel_hi:[1,0,1]
	v_cvt_scalef32_pk_f32_fp4 v[14:15], v26, 1.0 op_sel:[1,1,0]
	v_pk_fma_f32 v[70:71], v[72:73], v[0:1], v[70:71] op_sel:[0,1,0]
	v_cvt_scalef32_pk_f32_fp4 v[74:75], v18, 1.0 op_sel:[0,1,0]
	v_pk_fma_f32 v[12:13], v[8:9], v[124:125], v[12:13] op_sel_hi:[1,0,1]
	v_cvt_scalef32_pk_f32_fp4 v[8:9], v30, 1.0 op_sel:[1,1,0]
	v_pk_fma_f32 v[14:15], v[14:15], v[2:3], v[70:71] op_sel_hi:[1,0,1]
	v_cvt_scalef32_pk_f32_fp4 v[72:73], v22, 1.0 op_sel:[0,1,0]
	v_pk_fma_f32 v[68:69], v[74:75], v[0:1], v[68:69] op_sel_hi:[1,0,1]
	v_pk_fma_f32 v[70:71], v[8:9], v[124:125], v[14:15] op_sel_hi:[1,0,1]
	v_cvt_scalef32_pk_f32_fp4 v[14:15], v26, 1.0 op_sel:[0,1,0]
	v_pk_fma_f32 v[68:69], v[72:73], v[0:1], v[68:69] op_sel:[0,1,0]
	v_cvt_scalef32_pk_f32_fp4 v[74:75], v18, 1.0 op_sel:[1,0,0]
	v_cvt_scalef32_pk_f32_fp4 v[8:9], v30, 1.0 op_sel:[0,1,0]
	v_pk_fma_f32 v[14:15], v[14:15], v[2:3], v[68:69] op_sel_hi:[1,0,1]
	v_cvt_scalef32_pk_f32_fp4 v[72:73], v22, 1.0 op_sel:[1,0,0]
	v_pk_fma_f32 v[66:67], v[74:75], v[0:1], v[66:67] op_sel_hi:[1,0,1]
	v_pk_fma_f32 v[68:69], v[8:9], v[124:125], v[14:15] op_sel_hi:[1,0,1]
	v_cvt_scalef32_pk_f32_fp4 v[14:15], v26, 1.0 op_sel:[1,0,0]
	v_pk_fma_f32 v[66:67], v[72:73], v[0:1], v[66:67] op_sel:[0,1,0]
	v_cvt_scalef32_pk_f32_fp4 v[18:19], v18, 1.0
	v_cvt_scalef32_pk_f32_fp4 v[8:9], v30, 1.0 op_sel:[1,0,0]
	v_pk_fma_f32 v[14:15], v[14:15], v[2:3], v[66:67] op_sel_hi:[1,0,1]
	v_cvt_scalef32_pk_f32_fp4 v[22:23], v22, 1.0
	v_pk_fma_f32 v[18:19], v[18:19], v[0:1], v[64:65] op_sel_hi:[1,0,1]
	v_pk_fma_f32 v[66:67], v[8:9], v[124:125], v[14:15] op_sel_hi:[1,0,1]
	v_cvt_scalef32_pk_f32_fp4 v[14:15], v26, 1.0
	v_pk_fma_f32 v[18:19], v[22:23], v[0:1], v[18:19] op_sel:[0,1,0]
	v_cvt_scalef32_pk_f32_fp4 v[26:27], v17, 1.0 op_sel:[1,1,0]
	v_cvt_scalef32_pk_f32_fp4 v[8:9], v30, 1.0
	v_pk_fma_f32 v[14:15], v[14:15], v[2:3], v[18:19] op_sel_hi:[1,0,1]
	v_cvt_scalef32_pk_f32_fp4 v[22:23], v21, 1.0 op_sel:[1,1,0]
	v_pk_fma_f32 v[26:27], v[26:27], v[0:1], v[62:63] op_sel_hi:[1,0,1]
	v_pk_fma_f32 v[18:19], v[8:9], v[124:125], v[14:15] op_sel_hi:[1,0,1]
	v_cvt_scalef32_pk_f32_fp4 v[14:15], v25, 1.0 op_sel:[1,1,0]
	v_pk_fma_f32 v[22:23], v[22:23], v[0:1], v[26:27] op_sel:[0,1,0]
	v_cvt_scalef32_pk_f32_fp4 v[8:9], v29, 1.0 op_sel:[1,1,0]
	v_pk_fma_f32 v[14:15], v[14:15], v[2:3], v[22:23] op_sel_hi:[1,0,1]
	s_mul_i32 s11, s11, s33
	v_pk_fma_f32 v[22:23], v[8:9], v[124:125], v[14:15] op_sel_hi:[1,0,1]
	v_add_u32_e32 v8, s11, v172
	v_ashrrev_i32_e32 v3, 11, v8
	v_mul_i32_i24_e32 v14, 0x3000, v3
	v_ashrrev_i32_e32 v15, 31, v14
	v_lshl_add_u64 v[14:15], v[14:15], 2, s[72:73]
	v_lshl_add_u64 v[26:27], v[34:35], 2, v[14:15]
	v_ashrrev_i32_e32 v9, 31, v8
	v_add_co_u32_e32 v30, vcc, s80, v26
	v_lshlrev_b64 v[8:9], 13, v[8:9]
	s_nop 0
	v_addc_co_u32_e32 v31, vcc, 0, v27, vcc
	global_load_dwordx4 v[62:65], v[30:31], off offset:-4096
	v_lshl_add_u64 v[14:15], v[46:47], 0, v[8:9]
	global_load_dwordx4 v[72:75], v[14:15], off nt
	v_lshl_add_u64 v[26:27], v[26:27], 0, s[54:55]
	v_cvt_scalef32_pk_f32_fp4 v[80:81], v17, 1.0 op_sel:[0,1,0]
	global_load_dwordx4 v[76:79], v[26:27], off offset:1024
	v_pk_fma_f32 v[60:61], v[80:81], v[0:1], v[60:61] op_sel_hi:[1,0,1]
	global_load_dwordx4 v[80:83], v[14:15], off offset:1024 nt
	v_cvt_scalef32_pk_f32_fp4 v[86:87], v21, 1.0 op_sel:[0,1,0]
	v_cvt_scalef32_pk_f32_fp4 v[84:85], v25, 1.0 op_sel:[0,1,0]
	v_pk_fma_f32 v[60:61], v[86:87], v[0:1], v[60:61] op_sel:[0,1,0]
	v_cvt_scalef32_pk_f32_fp4 v[94:95], v17, 1.0 op_sel:[1,0,0]
	v_pk_fma_f32 v[60:61], v[84:85], v[2:3], v[60:61] op_sel_hi:[1,0,1]
	global_load_dwordx4 v[84:87], v[26:27], off offset:2048
	global_load_dwordx4 v[88:91], v[14:15], off offset:2048 nt
	v_cvt_scalef32_pk_f32_fp4 v[8:9], v29, 1.0 op_sel:[0,1,0]
	v_cvt_scalef32_pk_f32_fp4 v[92:93], v21, 1.0 op_sel:[1,0,0]
	v_pk_fma_f32 v[58:59], v[94:95], v[0:1], v[58:59] op_sel_hi:[1,0,1]
	v_pk_fma_f32 v[126:127], v[8:9], v[124:125], v[60:61] op_sel_hi:[1,0,1]
	v_cvt_scalef32_pk_f32_fp4 v[60:61], v25, 1.0 op_sel:[1,0,0]
	v_pk_fma_f32 v[58:59], v[92:93], v[0:1], v[58:59] op_sel:[0,1,0]
	v_cvt_scalef32_pk_f32_fp4 v[8:9], v29, 1.0 op_sel:[1,0,0]
	v_pk_fma_f32 v[96:97], v[60:61], v[2:3], v[58:59] op_sel_hi:[1,0,1]
	global_load_dwordx4 v[58:61], v[26:27], off offset:3072
	global_load_dwordx4 v[92:95], v[14:15], off offset:3072 nt
	v_pk_fma_f32 v[26:27], v[8:9], v[124:125], v[96:97] op_sel_hi:[1,0,1]
	v_add_co_u32_e32 v8, vcc, s63, v14
	global_load_dwordx4 v[96:99], v[30:31], off
	s_nop 0
	v_addc_co_u32_e32 v9, vcc, 0, v15, vcc
	global_load_dwordx4 v[100:103], v[8:9], off nt
	v_cvt_scalef32_pk_f32_fp4 v[104:105], v17, 1.0
	v_pk_fma_f32 v[56:57], v[104:105], v[0:1], v[56:57] op_sel_hi:[1,0,1]
	global_load_dwordx4 v[104:107], v[30:31], off offset:1024
	global_load_dwordx4 v[108:111], v[8:9], off offset:1024 nt
	v_cvt_scalef32_pk_f32_fp4 v[116:117], v21, 1.0
	v_cvt_scalef32_pk_f32_fp4 v[114:115], v25, 1.0
	v_pk_fma_f32 v[56:57], v[116:117], v[0:1], v[56:57] op_sel:[0,1,0]
	v_cvt_scalef32_pk_f32_fp4 v[112:113], v29, 1.0
	v_pk_fma_f32 v[56:57], v[114:115], v[2:3], v[56:57] op_sel_hi:[1,0,1]
	v_cvt_scalef32_pk_f32_fp4 v[122:123], v16, 1.0 op_sel:[1,1,0]
	v_pk_fma_f32 v[128:129], v[112:113], v[124:125], v[56:57] op_sel_hi:[1,0,1]
	global_load_dwordx4 v[112:115], v[30:31], off offset:2048
	global_load_dwordx4 v[116:119], v[8:9], off offset:2048 nt
	v_cvt_scalef32_pk_f32_fp4 v[120:121], v20, 1.0 op_sel:[1,1,0]
	v_pk_fma_f32 v[54:55], v[122:123], v[0:1], v[54:55] op_sel_hi:[1,0,1]
	v_cvt_scalef32_pk_f32_fp4 v[56:57], v24, 1.0 op_sel:[1,1,0]
	v_pk_fma_f32 v[54:55], v[120:121], v[0:1], v[54:55] op_sel:[0,1,0]
	v_cvt_scalef32_pk_f32_fp4 v[194:195], v16, 1.0 op_sel:[0,1,0]
	v_pk_fma_f32 v[132:133], v[56:57], v[2:3], v[54:55] op_sel_hi:[1,0,1]
	global_load_dwordx4 v[54:57], v[30:31], off offset:3072
	global_load_dwordx4 v[120:123], v[8:9], off offset:3072 nt
	v_cvt_scalef32_pk_f32_fp4 v[130:131], v28, 1.0 op_sel:[1,1,0]
	v_cvt_scalef32_pk_f32_fp4 v[134:135], v20, 1.0 op_sel:[0,1,0]
	v_pk_fma_f32 v[52:53], v[194:195], v[0:1], v[52:53] op_sel_hi:[1,0,1]
	v_cvt_scalef32_pk_f32_fp4 v[194:195], v16, 1.0 op_sel:[1,0,0]
	v_cvt_scalef32_pk_f32_fp4 v[16:17], v16, 1.0
	v_pk_fma_f32 v[30:31], v[130:131], v[124:125], v[132:133] op_sel_hi:[1,0,1]
	v_cvt_scalef32_pk_f32_fp4 v[132:133], v24, 1.0 op_sel:[0,1,0]
	v_pk_fma_f32 v[52:53], v[134:135], v[0:1], v[52:53] op_sel:[0,1,0]
	v_cvt_scalef32_pk_f32_fp4 v[134:135], v20, 1.0 op_sel:[1,0,0]
	v_pk_fma_f32 v[50:51], v[194:195], v[0:1], v[50:51] op_sel_hi:[1,0,1]
	v_cvt_scalef32_pk_f32_fp4 v[20:21], v20, 1.0
	v_pk_fma_f32 v[16:17], v[16:17], v[0:1], v[48:49] op_sel_hi:[1,0,1]
	v_cvt_scalef32_pk_f32_fp4 v[130:131], v28, 1.0 op_sel:[0,1,0]
	v_pk_fma_f32 v[52:53], v[132:133], v[2:3], v[52:53] op_sel_hi:[1,0,1]
	v_cvt_scalef32_pk_f32_fp4 v[132:133], v24, 1.0 op_sel:[1,0,0]
	v_pk_fma_f32 v[50:51], v[134:135], v[0:1], v[50:51] op_sel:[0,1,0]
	v_cvt_scalef32_pk_f32_fp4 v[24:25], v24, 1.0
	v_pk_fma_f32 v[0:1], v[20:21], v[0:1], v[16:17] op_sel:[0,1,0]
	v_pk_fma_f32 v[52:53], v[130:131], v[124:125], v[52:53] op_sel_hi:[1,0,1]
	v_cvt_scalef32_pk_f32_fp4 v[130:131], v28, 1.0 op_sel:[1,0,0]
	v_cvt_scalef32_pk_f32_fp4 v[28:29], v28, 1.0
	v_pk_fma_f32 v[0:1], v[24:25], v[2:3], v[0:1] op_sel_hi:[1,0,1]
	v_pk_fma_f32 v[50:51], v[132:133], v[2:3], v[50:51] op_sel_hi:[1,0,1]
	v_pk_fma_f32 v[16:17], v[28:29], v[124:125], v[0:1] op_sel_hi:[1,0,1]
	global_load_dwordx4 v[0:3], v[36:37], off
	v_pk_fma_f32 v[50:51], v[130:131], v[124:125], v[50:51] op_sel_hi:[1,0,1]
	v_mov_b32_e32 v28, v52
	v_mov_b32_e32 v21, v50
	v_mov_b32_e32 v29, v30
	v_mov_b32_e32 v30, v53
	s_waitcnt vmcnt(16)
	v_mov_b32_e32 v20, v62
	v_mov_b32_e32 v62, v16
	s_waitcnt vmcnt(15)
	v_pk_fma_f32 v[20:21], v[20:21], v[62:63], v[72:73]
	v_pk_fma_f32 v[28:29], v[28:29], v[64:65], v[74:75]
	v_pk_mul_f32 v[24:25], v[20:21], v[20:21]
	v_pk_mul_f32 v[48:49], v[28:29], v[28:29]
	s_waitcnt vmcnt(14)
	v_mov_b32_e32 v50, v76
	v_mov_b32_e32 v76, v17
	v_add_f32_e32 v24, v25, v24
	s_waitcnt vmcnt(13)
	v_pk_fma_f32 v[16:17], v[50:51], v[76:77], v[80:81]
	v_add_f32_e32 v24, v48, v24
	v_pk_mul_f32 v[50:51], v[16:17], v[16:17]
	v_add_f32_e32 v24, v49, v24
	v_pk_fma_f32 v[30:31], v[30:31], v[78:79], v[82:83]
	v_add_f32_e32 v24, v50, v24
	v_pk_mul_f32 v[52:53], v[30:31], v[30:31]
	v_mov_b32_e32 v62, v128
	v_mov_b32_e32 v63, v26
	v_add_f32_e32 v24, v51, v24
	s_waitcnt vmcnt(11)
	v_pk_fma_f32 v[62:63], v[62:63], v[84:85], v[88:89]
	v_add_f32_e32 v24, v52, v24
	v_pk_mul_f32 v[64:65], v[62:63], v[62:63]
	v_mov_b32_e32 v72, v126
	v_mov_b32_e32 v73, v22
	v_add_f32_e32 v24, v53, v24
	v_pk_fma_f32 v[72:73], v[72:73], v[86:87], v[90:91]
	v_add_f32_e32 v24, v64, v24
	v_pk_mul_f32 v[74:75], v[72:73], v[72:73]
	v_mov_b32_e32 v26, v129
	v_add_f32_e32 v24, v65, v24
	s_waitcnt vmcnt(9)
	v_pk_fma_f32 v[26:27], v[26:27], v[58:59], v[92:93]
	v_add_f32_e32 v24, v74, v24
	v_pk_mul_f32 v[58:59], v[26:27], v[26:27]
	v_mov_b32_e32 v22, v127
	v_add_f32_e32 v24, v75, v24
	v_pk_fma_f32 v[22:23], v[22:23], v[60:61], v[94:95]
	v_add_f32_e32 v24, v58, v24
	v_pk_mul_f32 v[60:61], v[22:23], v[22:23]
	v_mov_b32_e32 v76, v18
	v_mov_b32_e32 v77, v66
	v_add_f32_e32 v24, v59, v24
	s_waitcnt vmcnt(7)
	v_pk_fma_f32 v[76:77], v[76:77], v[96:97], v[100:101]
	v_add_f32_e32 v24, v60, v24
	v_pk_mul_f32 v[78:79], v[76:77], v[76:77]
	v_mov_b32_e32 v80, v68
	v_mov_b32_e32 v81, v70
	v_add_f32_e32 v24, v61, v24
	v_pk_fma_f32 v[80:81], v[80:81], v[98:99], v[102:103]
	v_add_f32_e32 v24, v78, v24
	v_pk_mul_f32 v[82:83], v[80:81], v[80:81]
	v_mov_b32_e32 v66, v19
	v_add_f32_e32 v24, v79, v24
	s_waitcnt vmcnt(5)
	v_pk_fma_f32 v[18:19], v[66:67], v[104:105], v[108:109]
	v_add_f32_e32 v24, v82, v24
	v_pk_mul_f32 v[66:67], v[18:19], v[18:19]
	v_mov_b32_e32 v70, v69
	v_add_f32_e32 v24, v83, v24
	v_pk_fma_f32 v[68:69], v[70:71], v[106:107], v[110:111]
	v_add_f32_e32 v24, v66, v24
	v_pk_mul_f32 v[70:71], v[68:69], v[68:69]
	v_mov_b32_e32 v84, v12
	v_mov_b32_e32 v85, v10
	v_add_f32_e32 v24, v67, v24
	s_waitcnt vmcnt(3)
	v_pk_fma_f32 v[84:85], v[84:85], v[112:113], v[116:117]
	v_add_f32_e32 v24, v70, v24
	v_pk_mul_f32 v[86:87], v[84:85], v[84:85]
	v_mov_b32_e32 v88, v6
	v_mov_b32_e32 v89, v4
	v_add_f32_e32 v24, v71, v24
	v_pk_fma_f32 v[88:89], v[88:89], v[114:115], v[118:119]
	v_add_f32_e32 v24, v86, v24
	v_pk_mul_f32 v[90:91], v[88:89], v[88:89]
	v_mov_b32_e32 v10, v13
	v_add_f32_e32 v24, v87, v24
	s_waitcnt vmcnt(1)
	v_pk_fma_f32 v[10:11], v[10:11], v[54:55], v[120:121]
	v_add_f32_e32 v24, v90, v24
	v_pk_mul_f32 v[12:13], v[10:11], v[10:11]
	v_mov_b32_e32 v4, v7
	v_add_f32_e32 v24, v91, v24
	v_pk_fma_f32 v[4:5], v[4:5], v[56:57], v[122:123]
	v_add_f32_e32 v12, v12, v24
	v_pk_mul_f32 v[6:7], v[4:5], v[4:5]
	v_add_f32_e32 v12, v13, v12
	v_add_f32_e32 v6, v6, v12
	v_add_f32_e32 v6, v7, v6
	s_nop 1
	v_add_f32_dpp v6, v6, v6 quad_perm:[1,0,3,2] row_mask:0xf bank_mask:0xf bound_ctrl:1
	s_nop 1
	v_add_f32_dpp v6, v6, v6 quad_perm:[2,3,0,1] row_mask:0xf bank_mask:0xf bound_ctrl:1
	s_nop 1
	v_add_f32_dpp v6, v6, v6 row_half_mirror row_mask:0xf bank_mask:0xf bound_ctrl:1
	s_nop 1
	v_add_f32_dpp v6, v6, v6 row_mirror row_mask:0xf bank_mask:0xf bound_ctrl:1
	v_mov_b32_e32 v7, v6
	s_nop 1
	v_permlane16_swap_b32_e32 v6, v7
	v_add_f32_e32 v6, v6, v7
	v_mov_b32_e32 v7, v6
	s_nop 1
	v_permlane32_swap_b32_e32 v6, v7
	v_add_f32_e32 v6, v6, v7
	v_fmamk_f32 v6, v6, 0x3a000000, v184
	v_mul_f32_e32 v7, 0x4b800000, v6
	v_cmp_gt_f32_e32 vcc, s64, v6
	s_nop 1
	v_cndmask_b32_e32 v6, v6, v7, vcc
	v_rsq_f32_e32 v6, v6
	s_nop 0
	v_mul_f32_e32 v7, 0x45800000, v6
	v_cndmask_b32_e32 v6, v6, v7, vcc
	v_pk_mul_f32 v[12:13], v[20:21], v[6:7] op_sel_hi:[1,0]
	v_pk_mul_f32 v[20:21], v[28:29], v[6:7] op_sel_hi:[1,0]
	s_waitcnt vmcnt(0)
	v_pk_mul_f32 v[0:1], v[0:1], v[12:13]
	v_pk_mul_f32 v[2:3], v[2:3], v[20:21]
	global_store_dwordx4 v[14:15], v[0:3], off nt
	global_load_dwordx4 v[0:3], v[36:37], off offset:1024
	v_pk_mul_f32 v[12:13], v[30:31], v[6:7] op_sel_hi:[1,0]
	v_pk_mul_f32 v[16:17], v[16:17], v[6:7] op_sel_hi:[1,0]
	v_pk_mul_f32 v[4:5], v[4:5], v[6:7] op_sel_hi:[1,0]
	s_waitcnt vmcnt(0)
	v_pk_mul_f32 v[0:1], v[0:1], v[16:17]
	v_pk_mul_f32 v[2:3], v[2:3], v[12:13]
	global_store_dwordx4 v[14:15], v[0:3], off offset:1024 nt
	global_load_dwordx4 v[0:3], v[36:37], off offset:2048
	v_pk_mul_f32 v[12:13], v[72:73], v[6:7] op_sel_hi:[1,0]
	v_pk_mul_f32 v[16:17], v[62:63], v[6:7] op_sel_hi:[1,0]
	s_waitcnt vmcnt(0)
	v_pk_mul_f32 v[2:3], v[2:3], v[12:13]
	v_pk_mul_f32 v[0:1], v[0:1], v[16:17]
	global_store_dwordx4 v[14:15], v[0:3], off offset:2048 nt
	global_load_dwordx4 v[0:3], v[36:37], off offset:3072
	v_pk_mul_f32 v[12:13], v[22:23], v[6:7] op_sel_hi:[1,0]
	v_pk_mul_f32 v[16:17], v[26:27], v[6:7] op_sel_hi:[1,0]
	s_waitcnt vmcnt(0)
	v_pk_mul_f32 v[2:3], v[2:3], v[12:13]
	v_pk_mul_f32 v[0:1], v[0:1], v[16:17]
	global_store_dwordx4 v[14:15], v[0:3], off offset:3072 nt
	global_load_dwordx4 v[0:3], v[38:39], off
	v_pk_mul_f32 v[12:13], v[80:81], v[6:7] op_sel_hi:[1,0]
	v_pk_mul_f32 v[14:15], v[76:77], v[6:7] op_sel_hi:[1,0]
	s_waitcnt vmcnt(0)
	v_pk_mul_f32 v[2:3], v[2:3], v[12:13]
	v_pk_mul_f32 v[0:1], v[0:1], v[14:15]
	global_store_dwordx4 v[8:9], v[0:3], off nt
	global_load_dwordx4 v[0:3], v[40:41], off
	v_pk_mul_f32 v[12:13], v[68:69], v[6:7] op_sel_hi:[1,0]
	v_pk_mul_f32 v[14:15], v[18:19], v[6:7] op_sel_hi:[1,0]
	s_waitcnt vmcnt(0)
	v_pk_mul_f32 v[2:3], v[12:13], v[2:3]
	v_pk_mul_f32 v[0:1], v[14:15], v[0:1]
	global_store_dwordx4 v[8:9], v[0:3], off offset:1024 nt
	global_load_dwordx4 v[0:3], v[42:43], off
	v_pk_mul_f32 v[12:13], v[88:89], v[6:7] op_sel_hi:[1,0]
	v_pk_mul_f32 v[14:15], v[84:85], v[6:7] op_sel_hi:[1,0]
	v_pk_mul_f32 v[6:7], v[10:11], v[6:7] op_sel_hi:[1,0]
	s_waitcnt vmcnt(0)
	v_pk_mul_f32 v[0:1], v[14:15], v[0:1]
	v_pk_mul_f32 v[2:3], v[12:13], v[2:3]
	global_store_dwordx4 v[8:9], v[0:3], off offset:2048 nt
	global_load_dwordx4 v[0:3], v[44:45], off
	s_waitcnt vmcnt(0)
	v_pk_mul_f32 v[0:1], v[6:7], v[0:1]
	v_pk_mul_f32 v[2:3], v[4:5], v[2:3]
	global_store_dwordx4 v[8:9], v[0:3], off offset:3072 nt
	s_branch .LBB0_806
